# seams before FFN1-down and FFN2-down panel-local as well (write-through conversion stores + counters) on top of the split seams
# speedup vs baseline: 1.0057x; 1.0052x over previous
; __device__ __forceinline__ void panel_sync(unsigned* cnt, int pm, int wid, int lane) {
;     asm volatile("s_waitcnt vmcnt(0) lgkmcnt(0)" ::: "memory"); __builtin_amdgcn_s_barrier(); asm volatile("" ::: "memory");
;     if (wid == 0) {
;         if (lane == 0) { __builtin_amdgcn_fence(__ATOMIC_RELEASE, "agent"); asm volatile("s_waitcnt vmcnt(0)" ::: "memory"); __hip_atomic_fetch_add(cnt + 64 * pm, 1u, __ATOMIC_RELAXED, __HIP_MEMORY_SCOPE_AGENT); }
;         unsigned sp = 0;
;         while ((unsigned)__builtin_amdgcn_readfirstlane(__hip_atomic_load(cnt + 64 * pm, __ATOMIC_RELAXED, __HIP_MEMORY_SCOPE_AGENT)) < 4u) { __builtin_amdgcn_s_sleep(2); if (++sp > (1u << 22)) break; }
;         __builtin_amdgcn_fence(__ATOMIC_ACQUIRE, "agent");
;         asm volatile("s_waitcnt vmcnt(0)" ::: "memory");
;     }
;     asm volatile("" ::: "memory"); __builtin_amdgcn_s_barrier(); asm volatile("" ::: "memory");
; }
.Lgb9_gpoll:
	global_load_dword v4, v0, s[12:13] sc1
	s_waitcnt vmcnt(0)
	v_readfirstlane_b32 s14, v4
	s_cmp_ge_u32 s14, 24
	s_cbranch_scc1 .Lgb9_gpanel
	s_sleep 1
	s_add_i32 s19, s19, 1
	s_cmp_lt_u32 s19, 20000
	s_cbranch_scc1 .Lgb9_gpoll
